# fox prologue batched gate loads, plus 3 s_nop so that all later code keeps the previous version's addresses
# speedup vs baseline: 1.0156x; 1.0156x over previous
; #define GAS __attribute__((address_space(1)))
; template <int MODE> ...
;     ...
;     u32x4 kreg = *(const GAS u32x4*)(kg + (size_t)t_first * 64 * LDH), vreg = *(const GAS u32x4*)(vg + (size_t)t_first * 64 * LDH);
;     float cq = 0.f;
;     if (MODE == 0) {
;         float lf[4];
; #pragma unroll
;         for (int i = 0; i < 4; ++i) { const float x = FL[(rowbase + 4 * tid + i) * 8] + bfv; lf[i] = (fminf(x, 0.f) - __logf(1.f + __expf(-fabsf(x)))) * L2E; }
;         const float s1 = lf[0], s2 = s1 + lf[1], s3 = s2 + lf[2], s4 = s3 + lf[3];
;         float v = s4;
; #pragma unroll
;         for (int off = 1; off < 64; off <<= 1) { const float n = __shfl_up(v, off); if (lane >= off) v += n; }
;         if (lane == 63) wt[wid] = v;
;         __syncthreads();
.LBB0_811:
	v_readlane_b32 s2, v254, 8
	s_mul_i32 s0, s2, 0x2aab
	s_lshr_b32 s1, s0, 31
	s_lshr_b32 s0, s0, 16
	s_add_i32 s0, s0, s1
	s_mul_i32 s1, s0, 6
	s_sub_i32 s4, s2, s1
	s_sext_i32_i16 s1, s4
	s_bfe_i64 s[4:5], s[4:5], 0x100000
	s_lshl_b32 s2, s1, 6
	s_lshl_b64 s[4:5], s[4:5], 2
	v_readlane_b32 s1, v252, 58
	s_add_u32 s8, s1, s4
	v_readlane_b32 s1, v252, 59
	s_addc_u32 s9, s1, s5
	s_add_u32 s4, s23, s4
	v_readlane_b32 s1, v252, 55
	s_addc_u32 s5, s1, s5
	v_mov_b32_e32 v1, v230
	global_load_dword v19, v0, s[4:5]
	s_ashr_i32 s3, s2, 31
	v_readfirstlane_b32 s1, v1
	s_ashr_i32 s6, s1, 6
	s_bfe_i64 s[0:1], s[0:1], 0x100000
	s_lshl_b64 s[4:5], s[0:1], 11
	v_readlane_b32 s0, v252, 56
	v_ashrrev_i32_e32 v18, 3, v1
	v_readlane_b32 s1, v252, 57
	v_add_u32_e32 v4, s4, v18
	v_lshlrev_b32_e32 v12, 2, v1
	v_mov_b64_e32 v[2:3], s[0:1]
	s_movk_i32 s0, 0x1880
	v_mad_i64_i32 v[2:3], s[0:1], v4, s0, v[2:3]
	v_lshlrev_b32_e32 v4, 3, v1
	v_ashrrev_i32_e32 v13, 31, v12
	v_and_b32_e32 v4, 56, v4
	v_lshl_add_u64 v[14:15], s[4:5], 0, v[12:13]
	v_lshl_add_u64 v[2:3], s[2:3], 1, v[2:3]
	v_lshlrev_b32_e32 v10, 1, v4
	v_mov_b32_e32 v11, v0
	v_lshlrev_b64 v[14:15], 5, v[14:15]
	v_lshl_add_u64 v[98:99], v[2:3], 0, v[10:11]
	v_lshl_add_u64 v[16:17], s[8:9], 0, v[14:15]
	global_load_dwordx4 v[2:5], v[98:99], off offset:768
	global_load_dwordx4 v[6:9], v[98:99], off offset:1536
	global_load_dword v11, v[16:17], off
	global_load_dword v176, v[16:17], off offset:32
	global_load_dword v177, v[16:17], off offset:64
	global_load_dword v179, v[16:17], off offset:96
	s_mov_b32 s8, 0xbfb8aa3b
	s_mov_b32 s7, 0x800000
	s_mov_b32 s9, 0x3f317217
	s_mov_b32 s10, 0x7f800000
	v_mov_b32_e32 v21, 0x41b17218
	s_waitcnt vmcnt(0)
	v_add_f32_e32 v11, v19, v11
	v_min_f32_e32 v13, 0, v11
	v_mul_f32_e64 v11, |v11|, s8
	v_exp_f32_e32 v11, v11
	s_nop 0
	v_add_f32_e32 v11, 1.0, v11
	v_cmp_gt_f32_e32 vcc, s7, v11
	s_nop 1
	v_cndmask_b32_e64 v14, 0, 32, vcc
	v_ldexp_f32 v11, v11, v14
	v_log_f32_e32 v11, v11
	s_nop 0
	v_mul_f32_e32 v14, 0x3f317217, v11
	v_fma_f32 v14, v11, s9, -v14
	v_fmac_f32_e32 v14, 0x3377d1cf, v11
	v_fmac_f32_e32 v14, 0x3f317217, v11
	v_cmp_lt_f32_e64 s[0:1], |v11|, s10
	s_nop 1
	v_cndmask_b32_e64 v11, v11, v14, s[0:1]
	v_cndmask_b32_e32 v14, 0, v21, vcc
	v_sub_f32_e32 v11, v11, v14
	v_sub_f32_e32 v11, v13, v11
	v_mul_f32_e32 v14, 0x3fb8aa3b, v11
	v_add_f32_e32 v11, v19, v176
	v_min_f32_e32 v13, 0, v11
	v_mul_f32_e64 v11, |v11|, s8
	v_exp_f32_e32 v11, v11
	s_nop 0
	v_add_f32_e32 v11, 1.0, v11
	v_cmp_gt_f32_e32 vcc, s7, v11
	s_nop 1
	v_cndmask_b32_e64 v15, 0, 32, vcc
	v_ldexp_f32 v11, v11, v15
	v_log_f32_e32 v11, v11
	s_nop 0
	v_mul_f32_e32 v15, 0x3f317217, v11
	v_fma_f32 v15, v11, s9, -v15
	v_fmac_f32_e32 v15, 0x3377d1cf, v11
	v_fmac_f32_e32 v15, 0x3f317217, v11
	v_cmp_lt_f32_e64 s[0:1], |v11|, s10
	s_nop 1
	v_cndmask_b32_e64 v11, v11, v15, s[0:1]
	v_cndmask_b32_e32 v15, 0, v21, vcc
	v_sub_f32_e32 v11, v11, v15
	v_sub_f32_e32 v13, v13, v11
	v_add_f32_e32 v11, v19, v177
	v_min_f32_e32 v15, 0, v11
	v_mul_f32_e64 v11, |v11|, s8
	v_exp_f32_e32 v11, v11
	s_nop 0
	v_add_f32_e32 v11, 1.0, v11
	v_cmp_gt_f32_e32 vcc, s7, v11
	s_nop 1
	v_cndmask_b32_e64 v20, 0, 32, vcc
	v_ldexp_f32 v11, v11, v20
	v_log_f32_e32 v11, v11
	s_nop 0
	v_mul_f32_e32 v20, 0x3f317217, v11
	v_fma_f32 v20, v11, s9, -v20
	v_fmac_f32_e32 v20, 0x3377d1cf, v11
	v_fmac_f32_e32 v20, 0x3f317217, v11
	v_cmp_lt_f32_e64 s[0:1], |v11|, s10
	s_nop 1
	v_cndmask_b32_e64 v11, v11, v20, s[0:1]
	v_cndmask_b32_e32 v20, 0, v21, vcc
	v_sub_f32_e32 v11, v11, v20
	v_sub_f32_e32 v20, v15, v11
	v_add_f32_e32 v11, v19, v179
	s_nop 0
	s_nop 0
	s_nop 0
	v_min_f32_e32 v15, 0, v11
	v_mul_f32_e64 v11, |v11|, s8
	v_exp_f32_e32 v11, v11
	v_add_u32_e32 v19, -1, v224
	v_add_f32_e32 v11, 1.0, v11
	v_cmp_gt_f32_e32 vcc, s7, v11
	s_nop 1
	v_cndmask_b32_e64 v16, 0, 32, vcc
	v_ldexp_f32 v11, v11, v16
	v_log_f32_e32 v11, v11
	s_nop 0
	v_mul_f32_e32 v16, 0x3f317217, v11
	v_fma_f32 v16, v11, s9, -v16
	v_fmac_f32_e32 v16, 0x3377d1cf, v11
	v_fmac_f32_e32 v16, 0x3f317217, v11
	v_cmp_lt_f32_e64 s[0:1], |v11|, s10
	s_nop 1
	v_cndmask_b32_e64 v11, v11, v16, s[0:1]
	v_cndmask_b32_e32 v16, 0, v21, vcc
	v_sub_f32_e32 v11, v11, v16
	v_sub_f32_e32 v17, v15, v11
	v_fmamk_f32 v15, v13, 0x3fb8aa3b, v14
	v_and_b32_e32 v13, 64, v224
	v_cmp_lt_i32_e32 vcc, v19, v13
	v_fmamk_f32 v16, v20, 0x3fb8aa3b, v15
	v_fmamk_f32 v17, v17, 0x3fb8aa3b, v16
	v_cndmask_b32_e32 v19, v19, v224, vcc
	v_lshlrev_b32_e32 v19, 2, v19
	ds_bpermute_b32 v19, v19, v17
	v_and_b32_e32 v11, 63, v1
	v_cmp_eq_u32_e32 vcc, 0, v11
	v_add_u32_e32 v20, -2, v224
	s_waitcnt lgkmcnt(0)
	v_add_f32_e32 v19, v17, v19
	v_cndmask_b32_e32 v19, v19, v17, vcc
	v_cmp_lt_i32_e32 vcc, v20, v13
	s_nop 1
	v_cndmask_b32_e32 v20, v20, v224, vcc
	v_lshlrev_b32_e32 v20, 2, v20
	ds_bpermute_b32 v20, v20, v19
	v_cmp_gt_u32_e32 vcc, 2, v11
	s_waitcnt lgkmcnt(0)
	v_add_f32_e32 v20, v19, v20
	v_cndmask_b32_e32 v19, v20, v19, vcc
	v_add_u32_e32 v20, -4, v224
	v_cmp_lt_i32_e32 vcc, v20, v13
	s_nop 1
	v_cndmask_b32_e32 v20, v20, v224, vcc
	v_lshlrev_b32_e32 v20, 2, v20
	ds_bpermute_b32 v20, v20, v19
	v_cmp_gt_u32_e32 vcc, 4, v11
	s_waitcnt lgkmcnt(0)
	v_add_f32_e32 v20, v19, v20
	v_cndmask_b32_e32 v19, v20, v19, vcc
	v_add_u32_e32 v20, -8, v224
	v_cmp_lt_i32_e32 vcc, v20, v13
	s_nop 1
	v_cndmask_b32_e32 v20, v20, v224, vcc
	v_lshlrev_b32_e32 v20, 2, v20
	ds_bpermute_b32 v20, v20, v19
	v_cmp_gt_u32_e32 vcc, 8, v11
	s_waitcnt lgkmcnt(0)
	v_add_f32_e32 v20, v19, v20
	v_cndmask_b32_e32 v19, v20, v19, vcc
	v_add_u32_e32 v20, -16, v224
	v_cmp_lt_i32_e32 vcc, v20, v13
	s_nop 1
	v_cndmask_b32_e32 v20, v20, v224, vcc
	v_lshlrev_b32_e32 v20, 2, v20
	ds_bpermute_b32 v20, v20, v19
	v_cmp_gt_u32_e32 vcc, 16, v11
	s_waitcnt lgkmcnt(0)
	v_add_f32_e32 v20, v19, v20
	v_cndmask_b32_e32 v19, v20, v19, vcc
	v_subrev_u32_e32 v20, 32, v224
	v_cmp_lt_i32_e32 vcc, v20, v13
	s_nop 1
	v_cndmask_b32_e32 v20, v20, v224, vcc
	v_lshlrev_b32_e32 v20, 2, v20
	ds_bpermute_b32 v20, v20, v19
	v_cmp_eq_u32_e32 vcc, 63, v11
	s_waitcnt lgkmcnt(0)
	v_add_f32_e32 v20, v19, v20
	s_and_saveexec_b64 s[0:1], vcc
	s_lshl_b32 s7, s6, 2
	s_add_i32 s7, s7, 0
	v_mov_b32_e32 v21, s7
	ds_write_b32 v21, v20 offset:45056
	s_or_b64 exec, exec, s[0:1]
	s_cmp_lt_i32 s6, 1
	s_waitcnt lgkmcnt(0)
	s_barrier
	s_cbranch_scc1 .LBB0_860
	ds_read_b32 v21, v0 offset:45056
	s_waitcnt lgkmcnt(0)
	v_add_f32_e32 v21, 0, v21
	s_cmp_lt_i32 s6, 2
	s_cbranch_scc1 .LBB0_816
